# work-queue counters sharded 8 ways by blockIdx&7 (64 contenders per counter instead of 512), ring of 3 counter sets re-zeroed one phase ahead
# speedup vs baseline: 1.0248x; 1.0094x over previous
.LBB0_5:
	s_ashr_i32 s15, s14, 31
	s_lshl_b64 s[0:1], s[14:15], 2
	v_readlane_b32 s2, v253, 23
	s_add_u32 s2, s2, s0
	v_readlane_b32 s0, v253, 24
	s_addc_u32 s3, s0, s1
	v_writelane_b32 v254, s2, 43
	s_mov_b32 s0, s14
	s_mov_b32 s28, 0x18000
	v_writelane_b32 v254, s3, 44
	v_writelane_b32 v254, s0, 45
	s_mov_b64 s[4:5], -1
	s_mov_b64 s[2:3], 0
	v_writelane_b32 v254, s1, 46
	s_cmp_lt_i32 s14, 2
	s_cbranch_scc1 .Lsh_skip
	s_mul_hi_u32 s98, s14, 0x55555556
	s_mul_i32 s98, s98, 3
	s_sub_i32 s98, s14, s98
	v_readlane_b32 s99, v254, 20
	s_and_b32 s99, s99, 7
	s_lshl_b32 s98, s98, 3
	s_add_i32 s98, s98, s99
	s_lshl_b32 s98, s98, 7
	s_add_i32 s98, s98, 0x3000
	v_readlane_b32 s0, v253, 17
	v_readlane_b32 s1, v253, 18
	s_add_u32 s0, s0, s98
	s_addc_u32 s1, s1, 0
	s_nop 0
	v_writelane_b32 v254, s0, 43
	v_writelane_b32 v254, s1, 44
	v_readlane_b32 s99, v254, 20
	s_cmp_lg_u32 s99, 0
	s_cbranch_scc1 .Lsh_skip
	s_add_i32 s98, s14, 1
	s_mul_hi_u32 s99, s98, 0x55555556
	s_mul_i32 s99, s99, 3
	s_sub_i32 s98, s98, s99
	s_lshl_b32 s98, s98, 10
	s_add_i32 s98, s98, 0x3000
	v_readlane_b32 s0, v253, 17
	v_readlane_b32 s1, v253, 18
	s_add_u32 s0, s0, s98
	s_addc_u32 s1, s1, 0
	s_and_saveexec_b64 s[98:99], s[12:13]
	global_store_dword v131, v131, s[0:1] sc1
	global_store_dword v131, v131, s[0:1] offset:128 sc1
	global_store_dword v131, v131, s[0:1] offset:256 sc1
	global_store_dword v131, v131, s[0:1] offset:384 sc1
	global_store_dword v131, v131, s[0:1] offset:512 sc1
	global_store_dword v131, v131, s[0:1] offset:640 sc1
	global_store_dword v131, v131, s[0:1] offset:768 sc1
	global_store_dword v131, v131, s[0:1] offset:896 sc1
	s_or_b64 exec, exec, s[98:99]
.Lsh_skip:
	s_cmp_lt_i32 s14, 1
	s_mov_b64 s[0:1], 0
	s_cbranch_scc1 .LBB0_68
	v_readlane_b32 s0, v254, 45
	v_readlane_b32 s1, v254, 46
	s_cmp_eq_u32 s0, 1
	s_mov_b64 s[0:1], -1
	s_cbranch_scc1 .LBB0_20

.LBB0_72:
	s_or_b64 exec, exec, s[0:1]
	s_waitcnt lgkmcnt(0)
	s_barrier
	ds_read_b32 v1, v161
	s_waitcnt lgkmcnt(0)
	v_readfirstlane_b32 s0, v1
	v_readlane_b32 s98, v255, 13
	s_lshl_b32 s0, s0, 3
	s_add_i32 s0, s0, s98
	v_readlane_b32 s98, v254, 20
	s_and_b32 s98, s98, 7
	s_add_i32 s0, s0, s98
	s_cmp_ge_i32 s0, s14
	s_cbranch_scc1 .LBB0_117

.LBB0_173:
	s_or_b64 exec, exec, s[0:1]
	s_waitcnt lgkmcnt(0)
	s_barrier
	ds_read_b32 v1, v161
	s_waitcnt lgkmcnt(0)
	v_readfirstlane_b32 s20, v1
	v_readlane_b32 s98, v255, 13
	s_lshl_b32 s20, s20, 3
	s_add_i32 s20, s20, s98
	v_readlane_b32 s98, v254, 20
	s_and_b32 s98, s98, 7
	s_add_i32 s20, s20, s98
	s_cmp_ge_i32 s20, s18
	s_cbranch_scc1 .LBB0_287

.LBB0_295:
	s_or_b64 exec, exec, s[2:3]
	s_waitcnt lgkmcnt(0)
	s_barrier
	ds_read_b32 v1, v161
	s_waitcnt lgkmcnt(0)
	v_readfirstlane_b32 s14, v1
	v_readlane_b32 s98, v255, 13
	s_lshl_b32 s14, s14, 3
	s_add_i32 s14, s14, s98
	v_readlane_b32 s98, v254, 20
	s_and_b32 s98, s98, 7
	s_add_i32 s14, s14, s98
	s_cmpk_gt_i32 s14, 0x83f
	s_cbranch_scc1 .LBB0_398

.LBB0_409:
	s_or_b64 exec, exec, s[0:1]
	s_waitcnt lgkmcnt(0)
	s_barrier
	ds_read_b32 v1, v161
	s_waitcnt lgkmcnt(0)
	v_readfirstlane_b32 s2, v1
	v_readlane_b32 s98, v255, 13
	s_lshl_b32 s2, s2, 3
	s_add_i32 s2, s2, s98
	v_readlane_b32 s98, v254, 20
	s_and_b32 s98, s98, 7
	s_add_i32 s2, s2, s98
	s_cmpk_gt_i32 s2, 0x113f
	s_cbranch_scc1 .LBB0_447

.LBB0_456:
	s_or_b64 exec, exec, s[0:1]
	s_waitcnt lgkmcnt(0)
	s_barrier
	ds_read_b32 v1, v161
	s_waitcnt lgkmcnt(0)
	v_readfirstlane_b32 s21, v1
	v_readlane_b32 s98, v255, 13
	s_lshl_b32 s21, s21, 3
	s_add_i32 s21, s21, s98
	v_readlane_b32 s98, v254, 20
	s_and_b32 s98, s98, 7
	s_add_i32 s21, s21, s98
	s_cmp_ge_i32 s21, s17
	s_cbranch_scc1 .LBB0_559

.LBB0_570:
	s_or_b64 exec, exec, s[4:5]
	s_waitcnt lgkmcnt(0)
	s_barrier
	ds_read_b32 v1, v161
	v_readlane_b32 s0, v254, 49
	s_waitcnt lgkmcnt(0)
	v_readfirstlane_b32 s18, v1
	v_readlane_b32 s98, v255, 13
	s_lshl_b32 s18, s18, 3
	s_add_i32 s18, s18, s98
	v_readlane_b32 s98, v254, 20
	s_and_b32 s98, s98, 7
	s_add_i32 s18, s18, s98
	s_cmp_ge_i32 s18, s0
	s_cbranch_scc1 .LBB0_740
